# split-phase seam 5: pool/bvec items first (remapped to consuming XCD, XCD-local dependency), global arrive after attention, wait moved before first mix GEMM epilogue
# speedup vs baseline: 1.0114x; 1.0085x over previous
.LBB0_836:
	s_mov_b32 s98, 0
	s_cmp_lt_i32 s68, 6
	s_cselect_b64 s[2:3], -1, 0
	s_and_b64 s[4:5], s[2:3], s[0:1]
	s_andn2_b64 vcc, exec, s[4:5]
	s_cbranch_vccnz .LBB0_1399
	v_mov_b32_e32 v0, 0x20050
	ds_read_b32 v0, v0
	s_mov_b32 s99, s80
	s_waitcnt lgkmcnt(0)
	v_readfirstlane_b32 s98, v0
	s_nop 3
	s_cmp_eq_u32 s98, 0
	s_cbranch_scc1 .Lp5_second
	s_mov_b32 s98, 1
	s_and_b32 s99, s38, 7
	s_lshl_b32 s99, s99, 5
	s_lshr_b32 s100, s38, 3
	s_add_i32 s99, s99, s100
	s_lshl_b32 s44, s99, 3
	s_add_i32 s44, s44, s23
	s_mov_b32 s22, s23
	v_lshlrev_b32_e32 v192, 3, v222
	s_branch .LBB0_1071
.Lp5_second:
	s_mov_b32 s24, s23
	v_readlane_b32 s8, v255, 3
	v_readlane_b32 s10, v255, 5
	v_readlane_b32 s11, v255, 6
	v_lshlrev_b32_e32 v2, 2, v199
	v_mov_b32_e32 v3, 0
	s_mov_b64 s[2:3], s[10:11]
	s_waitcnt lgkmcnt(0)
	v_lshl_add_u64 v[0:1], s[2:3], 0, v[2:3]
	s_movk_i32 s0, 0x1000
	v_add_co_u32_e32 v4, vcc, s0, v0
	v_or_b32_e32 v3, 0x1000, v2
	s_nop 0
	v_addc_co_u32_e32 v5, vcc, 0, v1, vcc
	v_or_b32_e32 v6, 0x2000, v2
	global_load_dword v7, v2, s[10:11]
	global_load_dword v8, v2, s[10:11] offset:2048
	global_load_dword v9, v3, s[10:11]
	global_load_dword v10, v[4:5], off offset:2048
	global_load_dword v11, v6, s[10:11]
	v_add_co_u32_e32 v4, vcc, 0x2000, v0
	s_movk_i32 s0, 0x288
	s_nop 0
	v_addc_co_u32_e32 v5, vcc, 0, v1, vcc
	global_load_dword v3, v[4:5], off offset:2048
	v_add_u32_e32 v2, 0, v2
	v_cmp_gt_u32_e32 vcc, s0, v199
	v_readlane_b32 s9, v255, 4
	v_readlane_b32 s12, v255, 7
	v_readlane_b32 s13, v255, 8
	v_readlane_b32 s14, v255, 9
	v_readlane_b32 s15, v255, 10
	v_readlane_b32 s16, v255, 11
	v_readlane_b32 s17, v255, 12
	v_readlane_b32 s18, v255, 13
	v_readlane_b32 s19, v255, 14
	v_readlane_b32 s20, v255, 15
	v_readlane_b32 s21, v255, 16
	v_readlane_b32 s22, v255, 17
	v_readlane_b32 s23, v255, 18
	s_waitcnt vmcnt(0)
	v_mul_f32_e32 v4, 0x3fb8aa3b, v7
	v_mul_f32_e32 v5, 0x3fb8aa3b, v8
	ds_write2st64_b32 v2, v4, v5 offset0:4 offset1:12
	v_mul_f32_e32 v4, 0x3fb8aa3b, v9
	v_mul_f32_e32 v5, 0x3fb8aa3b, v10
	v_mul_f32_e32 v6, 0x3fb8aa3b, v11
	ds_write2st64_b32 v2, v4, v5 offset0:20 offset1:28
	v_mul_f32_e32 v3, 0x3fb8aa3b, v3
	ds_write2st64_b32 v2, v6, v3 offset0:36 offset1:44
	s_and_saveexec_b64 s[0:1], vcc
	s_cbranch_execz .LBB0_840
	v_or_b32_e32 v3, 0xc00, v199
	v_readlane_b32 s8, v255, 3
	v_lshlrev_b32_e32 v4, 2, v3
	v_readlane_b32 s10, v255, 5
	v_readlane_b32 s11, v255, 6
	s_movk_i32 s2, 0xc88
	v_cmp_gt_u32_e32 vcc, s2, v3
	v_readlane_b32 s9, v255, 4
	v_readlane_b32 s12, v255, 7
	v_readlane_b32 s13, v255, 8
	global_load_dword v4, v4, s[10:11]
	v_readlane_b32 s14, v255, 9
	v_readlane_b32 s15, v255, 10
	v_readlane_b32 s16, v255, 11
	v_readlane_b32 s17, v255, 12
	v_readlane_b32 s18, v255, 13
	v_readlane_b32 s19, v255, 14
	v_readlane_b32 s20, v255, 15
	v_readlane_b32 s21, v255, 16
	v_readlane_b32 s22, v255, 17
	v_readlane_b32 s23, v255, 18
	s_waitcnt vmcnt(0)
	v_mul_f32_e32 v4, 0x3fb8aa3b, v4
	ds_write_b32 v2, v4 offset:13312
	s_and_saveexec_b64 s[2:3], vcc
	s_xor_b64 s[2:3], exec, s[2:3]
	s_cbranch_execz .LBB0_840
	v_add_co_u32_e32 v0, vcc, 0x3000, v0
	s_nop 1
	v_addc_co_u32_e32 v1, vcc, 0, v1, vcc
	global_load_dword v0, v[0:1], off offset:2048
	s_waitcnt vmcnt(0)
	v_mul_f32_e32 v0, 0x3fb8aa3b, v0
	ds_write_b32 v2, v0 offset:15360
.LBB0_840:
	s_or_b64 exec, exec, s[0:1]
	s_cmpk_gt_i32 s38, 0xff
	v_lshlrev_b32_e32 v192, 3, v222
	s_mov_b32 s22, s24
	s_waitcnt lgkmcnt(0)
	s_barrier
	s_cmp_eq_u32 s98, 2
	s_cbranch_scc0 .Lp5_noslot
	v_cmp_eq_u32_e32 vcc, 0, v199
	s_and_saveexec_b64 s[0:1], vcc
	s_cbranch_execz .Lp5_noslot_r
	v_mov_b32_e32 v0, 0x20048
	ds_read_b32 v0, v0
	s_lshl_b32 s2, s33, 7
	s_add_u32 s2, s2, 0x3600
	v_mov_b32_e32 v1, 7
	s_waitcnt lgkmcnt(0)
	v_lshl_add_u32 v0, v0, 2, s2
	global_store_dword v0, v1, s[92:93]

.Lp5_noslot:
	s_cmpk_gt_i32 s38, 0xff
	s_cbranch_scc1 .LBB0_1071
	s_add_u32 s2, s30, 0xcc00000
	s_addc_u32 s3, s31, 0
	s_add_u32 s16, s30, 0x3200000
	s_addc_u32 s17, s31, 0
	s_add_u32 s26, s30, 0xdc00000
	s_addc_u32 s27, s31, 0
	s_add_u32 s39, s30, 0x3000000
	s_addc_u32 s42, s31, 0
	s_add_u32 s43, s30, 0xec00000
	v_readlane_b32 s8, v255, 19
	s_addc_u32 s45, s31, 0
	s_bfe_u32 s47, s8, 0x10006
	s_lshl_b32 s0, s47, 5
	v_and_b32_e32 v1, 31, v199
	v_or_b32_e32 v193, s0, v1
	v_lshlrev_b32_e32 v0, 9, v1
	v_med3_u32 v1, v193, 8, 56
	v_add_u32_e32 v223, -8, v1
	v_mbcnt_lo_u32_b32 v1, -1, 0
	v_mov_b32_e32 v2, 0
	v_mbcnt_hi_u32_b32 v1, -1, v1
	v_lshrrev_b32_e32 v3, 5, v222
	v_lshlrev_b32_e32 v6, 4, v222
	v_mov_b32_e32 v7, v2
	v_and_b32_e32 v5, 64, v1
	s_lshr_b32 s46, s8, 7
	s_or_b32 s49, s0, 0x2000
	v_lshlrev_b32_e32 v4, 3, v3
	v_lshl_add_u64 v[6:7], s[30:31], 0, v[6:7]
	s_mov_b64 s[6:7], 0xe400000
	v_lshlrev_b32_e32 v198, 2, v3
	v_xor_b32_e32 v3, 32, v1
	v_add_u32_e32 v5, 64, v5
	v_lshl_add_u64 v[194:195], v[6:7], 0, s[6:7]
	s_mov_b64 s[6:7], 0xf400000
	s_bitcmp1_b32 s8, 6
	v_cmp_lt_i32_e32 vcc, v3, v5
	s_mov_b32 s1, 0
	v_lshl_add_u64 v[196:197], v[6:7], 0, s[6:7]
	s_cselect_b64 s[6:7], -1, 0
	v_cndmask_b32_e32 v1, v1, v3, vcc
	s_lshl_b32 s0, s22, 5
	v_lshlrev_b32_e32 v200, 1, v0
	v_lshlrev_b32_e32 v204, 1, v4
	v_lshlrev_b32_e32 v208, 1, v192
	s_movk_i32 s48, 0x2000
	v_lshlrev_b32_e32 v224, 2, v1
	s_lshl_b64 s[8:9], s[0:1], 9
	v_mov_b32_e32 v202, v200
	v_mov_b32_e32 v203, v2
	v_mov_b32_e32 v206, v204
	v_mov_b32_e32 v207, v2
	v_mov_b32_e32 v210, v208
	v_mov_b32_e32 v211, v2
	s_mov_b64 s[12:13], 0x1000
	s_movk_i32 s50, 0x1000
	s_mov_b32 s51, 0x3e38aa3b
	s_movk_i32 s52, 0xffef
	v_lshlrev_b32_e32 v212, 1, v198
	s_mov_b32 s53, 0xf149f2ca
	s_movk_i32 s54, 0x3000
	s_movk_i32 s55, 0x4000
	s_movk_i32 s56, 0x5000
	s_movk_i32 s57, 0x6000
	s_movk_i32 s58, 0x7000
	v_mov_b32_e32 v225, 0xf149f2ca
	s_mov_b32 s14, s38
	s_branch .LBB0_843

.LBB0_1071:
	s_cmp_eq_u32 s98, 2
	s_cbranch_scc1 .LBB0_1399
	s_cmpk_gt_i32 s44, 0x7ff
	s_cbranch_scc1 .LBB0_1394
	v_readlane_b32 s0, v255, 19
	s_bfe_u32 s6, s0, 0x20006
	s_lshl_b32 s0, s6, 9
	s_add_u32 s2, s30, s0
	s_addc_u32 s3, s31, 0
	v_mov_b32_e32 v193, 0
	v_lshl_add_u64 v[0:1], s[2:3], 0, v[192:193]
	s_mov_b64 s[2:3], 0xac00000
	s_lshl_b32 s0, s6, 8
	v_lshl_add_u64 v[0:1], v[0:1], 0, s[2:3]
	s_add_u32 s2, s30, s0
	s_addc_u32 s3, s31, 0
	v_lshlrev_b32_e32 v192, 2, v222
	v_lshl_add_u64 v[2:3], s[2:3], 0, v[192:193]
	s_mov_b64 s[2:3], 0x9400000
	v_lshl_add_u64 v[2:3], v[2:3], 0, s[2:3]
	s_lshl_b32 s0, s99, 6
	s_lshl_b32 s2, s22, 3
	s_mov_b32 s1, 0
	s_add_i32 s7, s0, s2
	s_lshl_b32 s8, s34, 6
	s_movk_i32 s9, 0xe0
	s_movk_i32 s10, 0x100
	s_mov_b32 s11, s44
	s_branch .LBB0_1075

.LBB0_1399:
	s_cmp_eq_u32 s98, 1
	s_cbranch_scc0 .Lp5_tail
	s_mov_b32 s98, 2
	s_branch .Lp5_second
.Lp5_tail:
	s_cmp_gt_i32 s69, 6
	s_cselect_b64 s[0:1], -1, 0
	s_and_b64 s[2:3], s[4:5], s[0:1]
	s_andn2_b64 vcc, exec, s[2:3]
	s_cbranch_vccnz .LBB0_1453
	s_cmp_eq_u32 s98, 2
	s_cbranch_scc0 .Lsb_orig
	s_waitcnt vmcnt(0) lgkmcnt(0)
	s_barrier
	s_mov_b32 s98, 3
	v_cmp_gt_u32_e32 vcc, 64, v199
	s_cbranch_vccz .Lsb_done
	s_lshl_b32 s6, s33, 8
	s_add_u32 s6, s92, s6
	s_addc_u32 s7, s93, 0
	v_mov_b32_e32 v0, 0x1400
	v_mov_b32_e32 v1, 1
	s_lshl_b32 s10, s33, 7
	s_add_u32 s10, s10, 0x3600
	v_lshl_add_u32 v4, v199, 2, s10
	v_cmp_eq_u32_e32 vcc, 0, v199
	s_and_saveexec_b64 s[12:13], vcc
	global_atomic_add v2, v0, v1, s[6:7] sc0
	s_mov_b64 exec, s[12:13]
	s_waitcnt vmcnt(0)
	v_readfirstlane_b32 s11, v2
	s_nop 3
	s_lshr_b32 s99, s11, 5
	s_and_b32 s11, s11, 31
	s_cmp_eq_u32 s11, 31
	s_cbranch_scc0 .Lsb_waitA
	buffer_wbl2 sc1
	s_waitcnt vmcnt(0)
	v_mov_b32_e32 v0, 0xfc03000
	s_and_saveexec_b64 s[12:13], vcc
	global_atomic_add v2, v0, v1, s[30:31] offset:1024 sc0
	s_mov_b64 exec, s[12:13]
	s_waitcnt vmcnt(0)
	v_readfirstlane_b32 s11, v2
	s_nop 3
	s_and_b32 s11, s11, 7
	s_cmp_eq_u32 s11, 7
	s_cbranch_scc0 .Lsb_waitA
	v_mov_b32_e32 v0, 0xfc03500
	s_and_saveexec_b64 s[12:13], vcc
	global_atomic_add v0, v1, s[30:31]
	s_mov_b64 exec, s[12:13]
.Lsb_waitA:
	v_cmp_gt_u32_e32 vcc, 32, v199
	s_and_saveexec_b64 s[12:13], vcc
	s_mov_b32 s14, 0x8000
.Lsb_pollA:
	global_load_dword v5, v4, s[92:93] sc1
	s_waitcnt vmcnt(0)
	v_cmp_gt_u32_e32 vcc, 7, v5
	s_cbranch_vccz .Lsb_gotA
	s_sleep 1
	s_sub_u32 s14, s14, 1
	s_cmp_lg_u32 s14, 0
	s_cbranch_scc1 .Lsb_pollA
.Lsb_gotA:
	s_mov_b64 exec, s[12:13]
	buffer_inv sc1
	s_waitcnt vmcnt(0)
.Lsb_done:
	s_barrier
	s_branch .LBB0_1453
.Lsb_orig:
	s_waitcnt vmcnt(0)
	s_waitcnt vmcnt(0) lgkmcnt(0)
	s_barrier
	s_mov_b64 s[2:3], exec
	v_readlane_b32 s4, v255, 1
	v_readlane_b32 s5, v255, 2
	s_and_b64 s[4:5], s[2:3], s[4:5]
	s_mov_b64 exec, s[4:5]
	s_cbranch_execz .LBB0_1452
	s_add_i32 s4, 0, 0x20040
	v_mov_b32_e32 v0, s4
	s_waitcnt vmcnt(0) expcnt(0) lgkmcnt(0)
	ds_read_b32 v2, v0
	s_add_i32 s4, 0, 0x20044
	v_mov_b32_e32 v0, s4
	ds_read_b32 v0, v0
	s_waitcnt lgkmcnt(1)
	v_cmp_ne_u32_e32 vcc, 0, v2
	s_cbranch_vccnz .LBB0_1416
	v_readlane_b32 s4, v255, 0
	s_mul_i32 s16, s35, s4
	s_add_u32 s4, s30, 0xfc00200
	s_addc_u32 s5, s31, 0
	s_add_u32 s6, s30, 0xfc00400
	s_addc_u32 s7, s31, 0
	s_add_u32 s8, s30, 0xfc00500
	s_addc_u32 s9, s31, 0
	s_add_u32 s12, s30, 0xfc00600
	s_addc_u32 s13, s31, 0
	s_add_u32 s14, s30, 0xfc00700
	s_addc_u32 s15, s31, 0
	s_add_u32 s18, s30, 0xfc00800
	s_addc_u32 s19, s31, 0
	s_add_u32 s20, s30, 0xfc00900
	s_addc_u32 s21, s31, 0
	s_add_u32 s24, s30, 0xfc00a00
	s_addc_u32 s25, s31, 0
	s_add_u32 s26, s30, 0xfc00b00
	s_addc_u32 s27, s31, 0
	s_add_u32 s42, s30, 0xfc00c00
	s_addc_u32 s43, s31, 0
	s_add_u32 s44, s30, 0xfc00d00
	s_addc_u32 s45, s31, 0
	s_add_u32 s46, s30, 0xfc00e00
	s_addc_u32 s47, s31, 0
	s_add_u32 s48, s30, 0xfc00f00
	s_addc_u32 s49, s31, 0
	s_add_u32 s50, s30, 0xfc01000
	s_addc_u32 s51, s31, 0
	s_add_u32 s52, s30, 0xfc01100
	s_addc_u32 s53, s31, 0
	s_add_u32 s54, s30, 0xfc01200
	s_addc_u32 s55, s31, 0
	s_add_u32 s56, s30, 0xfc01300
	s_mul_i32 s16, s16, s34
	s_addc_u32 s57, s31, 0
	s_mov_b32 s17, 1
	v_mov_b32_e32 v16, 0
	s_branch .LBB0_1404

.LBB0_1474:
	s_cmp_eq_u32 s98, 3
	s_cbranch_scc0 .Lwb_skip
	s_mov_b32 s98, 4
	v_cmp_gt_u32_e32 vcc, 64, v199
	s_cbranch_vccz .Lwb_bar
	v_mov_b32_e32 v176, 0xfc03500
	s_mov_b32 s100, 0x8000
.Lwb_poll:
	global_load_dword v177, v176, s[30:31] sc1
	s_waitcnt vmcnt(0)
	v_cmp_lt_u32_e32 vcc, s99, v177
	s_cbranch_vccnz .Lwb_got
	s_sleep 1
	s_sub_u32 s100, s100, 1
	s_cmp_lg_u32 s100, 0
	s_cbranch_scc1 .Lwb_poll
.Lwb_got:
	buffer_inv sc1
	s_waitcnt vmcnt(0)
.Lwb_bar:
	s_barrier

	.amdhsa_kernel _Z6mk_fwd4Args
		.amdhsa_group_segment_fixed_size 0
		.amdhsa_private_segment_fixed_size 0
		.amdhsa_kernarg_size 472
		.amdhsa_user_sgpr_count 2
		.amdhsa_user_sgpr_dispatch_ptr 0
		.amdhsa_user_sgpr_queue_ptr 0
		.amdhsa_user_sgpr_kernarg_segment_ptr 1
		.amdhsa_user_sgpr_dispatch_id 0
		.amdhsa_user_sgpr_kernarg_preload_length 0
		.amdhsa_user_sgpr_kernarg_preload_offset 0
		.amdhsa_user_sgpr_private_segment_size 0
		.amdhsa_uses_dynamic_stack 0
		.amdhsa_enable_private_segment 0
		.amdhsa_system_sgpr_workgroup_id_x 1
		.amdhsa_system_sgpr_workgroup_id_y 0
		.amdhsa_system_sgpr_workgroup_id_z 0
		.amdhsa_system_sgpr_workgroup_info 0
		.amdhsa_system_vgpr_workitem_id 2
		.amdhsa_next_free_vgpr 256
		.amdhsa_next_free_sgpr 102
		.amdhsa_accum_offset 256
		.amdhsa_reserve_vcc 1
		.amdhsa_float_round_mode_32 0
		.amdhsa_float_round_mode_16_64 0
		.amdhsa_float_denorm_mode_32 3
		.amdhsa_float_denorm_mode_16_64 3
		.amdhsa_dx10_clamp 1
		.amdhsa_ieee_mode 1
		.amdhsa_fp16_overflow 0
		.amdhsa_tg_split 0
		.amdhsa_exception_fp_ieee_invalid_op 0
		.amdhsa_exception_fp_denorm_src 0
		.amdhsa_exception_fp_ieee_div_zero 0
		.amdhsa_exception_fp_ieee_overflow 0
		.amdhsa_exception_fp_ieee_underflow 0
		.amdhsa_exception_fp_ieee_inexact 0
		.amdhsa_exception_int_div_zero 0
	.end_amdhsa_kernel

amdhsa.kernels:
  - .agpr_count:     0
    .args:
      - .offset:         0
        .size:           216
        .value_kind:     by_value
      - .offset:         216
        .size:           4
        .value_kind:     hidden_block_count_x
      - .offset:         220
        .size:           4
        .value_kind:     hidden_block_count_y
      - .offset:         224
        .size:           4
        .value_kind:     hidden_block_count_z
      - .offset:         228
        .size:           2
        .value_kind:     hidden_group_size_x
      - .offset:         230
        .size:           2
        .value_kind:     hidden_group_size_y
      - .offset:         232
        .size:           2
        .value_kind:     hidden_group_size_z
      - .offset:         234
        .size:           2
        .value_kind:     hidden_remainder_x
      - .offset:         236
        .size:           2
        .value_kind:     hidden_remainder_y
      - .offset:         238
        .size:           2
        .value_kind:     hidden_remainder_z
      - .offset:         256
        .size:           8
        .value_kind:     hidden_global_offset_x
      - .offset:         264
        .size:           8
        .value_kind:     hidden_global_offset_y
      - .offset:         272
        .size:           8
        .value_kind:     hidden_global_offset_z
      - .offset:         280
        .size:           2
        .value_kind:     hidden_grid_dims
      - .offset:         304
        .size:           8
        .value_kind:     hidden_multigrid_sync_arg
      - .offset:         336
        .size:           4
        .value_kind:     hidden_dynamic_lds_size
    .group_segment_fixed_size: 0
    .kernarg_segment_align: 8
    .kernarg_segment_size: 472
    .language:       OpenCL C
    .language_version:
      - 2
      - 0
    .max_flat_workgroup_size: 512
    .name:           _Z6mk_fwd4Args
    .private_segment_fixed_size: 0
    .sgpr_count:     108
    .sgpr_spill_count: 42
    .symbol:         _Z6mk_fwd4Args.kd
    .uniform_work_group_size: 1
    .uses_dynamic_stack: false
    .vgpr_count:     256
    .vgpr_spill_count: 0
    .wavefront_size: 64
